# attention: rare mask / rescale / O-rescale blocks moved out of line so the common path falls through (on top of v7)
# speedup vs baseline: 1.0039x; 1.0039x over previous
.Latt_prio_done:
.LBB0_674:
	s_add_i32 s2, s67, -1
	s_and_b32 s2, s2, 3
	s_mulk_i32 s2, 0x3400
	s_and_b32 s71, s67, 2
	s_add_i32 s2, s2, 0
	s_xor_b32 s3, s71, 2
	v_add_u32_e32 v0, s2, v192
	s_mulk_i32 s3, 0x2400
	s_waitcnt vmcnt(5)
	ds_write_b128 v0, v[152:155]
	v_add_u32_e32 v0, s2, v185
	s_add_i32 s2, s67, 5
	s_waitcnt vmcnt(4)
	ds_write_b128 v0, v[156:159] offset:128
	v_add_u32_e32 v0, s3, v193
	s_min_i32 s46, s2, s66
	s_add_i32 s2, s67, 4
	v_add_u32_e32 v0, 0xd000, v0
	s_min_i32 s2, s2, s66
	s_lshl_b64 s[4:5], s[46:47], 16
	s_mov_b32 s3, s47
	s_waitcnt vmcnt(3)
	ds_write2_b64 v0, v[172:173], v[174:175] offset1:2
	v_lshl_add_u64 v[2:3], v[186:187], 0, s[4:5]
	s_lshl_b64 s[4:5], s[46:47], 12
	s_lshl_b64 s[2:3], s[2:3], 7
	v_lshl_add_u64 v[4:5], v[188:189], 0, s[4:5]
	global_load_dwordx4 v[152:155], v[2:3], off
	global_load_dwordx4 v[156:159], v[4:5], off
	v_lshl_add_u64 v[2:3], v[190:191], 0, s[2:3]
	global_load_dwordx4 v[172:175], v[2:3], off
	s_add_i32 s70, s67, 1
	s_and_b32 s69, s70, 3
	s_cmp_gt_i32 s67, s65
	s_cbranch_scc1 .LBB0_685
	s_mul_i32 s2, s69, 0x3400
	v_add_u32_e32 v0, s2, v196
	ds_read_b128 v[2:5], v0
	ds_read_b128 v[6:9], v0 offset:6656
	s_waitcnt lgkmcnt(1)
	v_mfma_f32_32x32x16_bf16 v[112:127], v[2:5], v[128:131], v[48:63]
	ds_read_b128 v[10:13], v0 offset:32
	ds_read_b128 v[202:205], v0 offset:6688
	v_add_f32_e32 v14, 0, v80
	v_add_f32_e32 v14, v81, v14
	v_cvt_pk_bf16_f32 v176, v80, v81
	s_waitcnt lgkmcnt(2)
	v_mfma_f32_32x32x16_bf16 v[96:111], v[6:9], v[128:131], v[48:63]
	v_add_f32_e32 v2, v82, v14
	v_add_f32_e32 v2, v83, v2
	v_add_f32_e32 v14, v84, v2
	v_cvt_pk_bf16_f32 v177, v82, v83
	s_waitcnt lgkmcnt(1)
	v_mfma_f32_32x32x16_bf16 v[112:127], v[10:13], v[132:135], v[112:127]
	ds_read_b128 v[2:5], v0 offset:64
	ds_read_b128 v[6:9], v0 offset:6720
	v_add_f32_e32 v14, v85, v14
	v_add_f32_e32 v14, v86, v14
	v_add_f32_e32 v14, v87, v14
	v_cvt_pk_bf16_f32 v178, v84, v85
	v_cvt_pk_bf16_f32 v179, v86, v87
	s_waitcnt lgkmcnt(2)
	v_mfma_f32_32x32x16_bf16 v[96:111], v[202:205], v[132:135], v[96:111]
	v_add_f32_e32 v10, v88, v14
	v_add_f32_e32 v11, v89, v10
	v_cvt_pk_bf16_f32 v10, v88, v89
	s_waitcnt lgkmcnt(1)
	v_mfma_f32_32x32x16_bf16 v[112:127], v[2:5], v[136:139], v[112:127]
	ds_read_b128 v[80:83], v0 offset:96
	ds_read_b128 v[202:205], v0 offset:6752
	v_add_f32_e32 v11, v90, v11
	v_add_f32_e32 v11, v91, v11
	v_add_f32_e32 v12, v92, v11
	v_cvt_pk_bf16_f32 v11, v90, v91
	s_waitcnt lgkmcnt(2)
	v_mfma_f32_32x32x16_bf16 v[96:111], v[6:9], v[136:139], v[96:111]
	v_add_f32_e32 v2, v93, v12
	v_add_f32_e32 v2, v94, v2
	v_add_f32_e32 v14, v95, v2
	v_cvt_pk_bf16_f32 v12, v92, v93
	v_cvt_pk_bf16_f32 v13, v94, v95
	s_waitcnt lgkmcnt(1)
	v_mfma_f32_32x32x16_bf16 v[112:127], v[80:83], v[140:143], v[112:127]
	ds_read_b128 v[2:5], v0 offset:128
	ds_read_b128 v[206:209], v0 offset:6784
	v_add_f32_e32 v6, v16, v14
	v_add_f32_e32 v7, v17, v6
	v_cvt_pk_bf16_f32 v6, v16, v17
	s_waitcnt lgkmcnt(2)
	v_mfma_f32_32x32x16_bf16 v[96:111], v[202:205], v[140:143], v[96:111]
	v_add_f32_e32 v7, v18, v7
	v_add_f32_e32 v7, v19, v7
	v_add_f32_e32 v8, v20, v7
	v_cvt_pk_bf16_f32 v7, v18, v19
	s_waitcnt lgkmcnt(1)
	v_mfma_f32_32x32x16_bf16 v[112:127], v[2:5], v[144:147], v[112:127]
	ds_read_b128 v[14:17], v0 offset:160
	ds_read_b128 v[80:83], v0 offset:6816
	v_add_f32_e32 v0, v21, v8
	v_add_f32_e32 v0, v22, v0
	v_add_f32_e32 v0, v23, v0
	v_cvt_pk_bf16_f32 v8, v20, v21
	v_cvt_pk_bf16_f32 v9, v22, v23
	s_waitcnt lgkmcnt(2)
	v_mfma_f32_32x32x16_bf16 v[96:111], v[206:209], v[144:147], v[96:111]
	v_add_f32_e32 v0, v24, v0
	v_add_f32_e32 v0, v25, v0
	v_cvt_pk_bf16_f32 v2, v24, v25
	s_waitcnt lgkmcnt(1)
	v_mfma_f32_32x32x16_bf16 v[112:127], v[14:17], v[148:151], v[112:127]
	v_add_f32_e32 v0, v26, v0
	v_add_f32_e32 v0, v27, v0
	v_add_f32_e32 v0, v28, v0
	v_cvt_pk_bf16_f32 v3, v26, v27
	s_waitcnt lgkmcnt(0)
	v_mfma_f32_32x32x16_bf16 v[96:111], v[80:83], v[148:151], v[96:111]
	v_add_f32_e32 v0, v29, v0
	v_add_f32_e32 v0, v30, v0
	v_add_f32_e32 v0, v31, v0
	v_cvt_pk_bf16_f32 v4, v28, v29
	v_cvt_pk_bf16_f32 v5, v30, v31
	s_mul_i32 s4, s71, 0x2400
	v_add_u32_e32 v206, s4, v200
	ds_read_b128 v[16:19], v206 offset:53248
	ds_read_b128 v[202:205], v206 offset:57856
	s_cmp_ge_i32 s67, s65
	v_add_f32_e32 v201, v201, v0
	s_cbranch_scc1 .LBB0_682
	s_sub_i32 s2, s68, 64
	s_cmp_le_i32 s2, s63
	s_cbranch_scc0 .Latt_mask0
.LBB0_680:
	v_max_f32_e32 v0, v113, v113
	v_max_f32_e32 v14, v112, v112
	v_max_f32_e32 v0, v14, v0
	v_max3_f32 v14, v114, v115, v97
	v_max3_f32 v0, v0, v96, v98
	v_max3_f32 v0, v0, v99, v116
	v_max3_f32 v14, v14, v118, v119
	v_max3_f32 v0, v0, v117, v100
	v_max3_f32 v14, v14, v102, v103
	v_max3_f32 v0, v0, v101, v120
	v_max3_f32 v14, v14, v122, v123
	v_max3_f32 v0, v0, v121, v104
	v_max3_f32 v14, v14, v106, v107
	v_max3_f32 v0, v0, v105, v124
	v_max3_f32 v14, v14, v126, v127
	v_max3_f32 v0, v0, v125, v108
	v_max3_f32 v14, v14, v110, v111
	v_max3_f32 v0, v0, v109, v14
	v_cmp_lt_f32_e32 vcc, s60, v0
	s_cbranch_vccnz .Latt_resc0

.LBB0_683:
	s_waitcnt lgkmcnt(1)
	v_mfma_f32_32x32x16_bf16 v[64:79], v[16:19], v[176:179], v[64:79]
	v_exp_f32_e32 v80, v112
	v_exp_f32_e32 v81, v113
	v_exp_f32_e32 v82, v114
	v_exp_f32_e32 v83, v115
	ds_read_b128 v[112:115], v206 offset:53280
	s_waitcnt lgkmcnt(1)
	v_mfma_f32_32x32x16_bf16 v[32:47], v[202:205], v[176:179], v[32:47]
	ds_read_b128 v[14:17], v206 offset:57888
	v_exp_f32_e32 v84, v116
	v_exp_f32_e32 v85, v117
	v_exp_f32_e32 v86, v118
	v_exp_f32_e32 v87, v119
	s_waitcnt lgkmcnt(1)
	v_mfma_f32_32x32x16_bf16 v[64:79], v[112:115], v[10:13], v[64:79]
	ds_read_b128 v[116:119], v206 offset:53312
	v_exp_f32_e32 v88, v120
	v_exp_f32_e32 v89, v121
	v_exp_f32_e32 v90, v122
	v_exp_f32_e32 v91, v123
	s_waitcnt lgkmcnt(1)
	v_mfma_f32_32x32x16_bf16 v[32:47], v[14:17], v[10:13], v[32:47]
	ds_read_b128 v[112:115], v206 offset:57920
	v_exp_f32_e32 v92, v124
	v_exp_f32_e32 v93, v125
	v_exp_f32_e32 v94, v126
	v_exp_f32_e32 v95, v127
	s_waitcnt lgkmcnt(1)
	v_mfma_f32_32x32x16_bf16 v[64:79], v[116:119], v[6:9], v[64:79]
	ds_read_b128 v[10:13], v206 offset:53344
	v_exp_f32_e32 v16, v96
	v_exp_f32_e32 v17, v97
	v_exp_f32_e32 v18, v98
	v_exp_f32_e32 v19, v99
	s_waitcnt lgkmcnt(1)
	v_mfma_f32_32x32x16_bf16 v[32:47], v[112:115], v[6:9], v[32:47]
	ds_read_b128 v[96:99], v206 offset:57952
	v_exp_f32_e32 v20, v100
	v_exp_f32_e32 v21, v101
	v_exp_f32_e32 v22, v102
	v_exp_f32_e32 v23, v103
	s_waitcnt lgkmcnt(1)
	v_mfma_f32_32x32x16_bf16 v[64:79], v[10:13], v[2:5], v[64:79]
	v_exp_f32_e32 v24, v104
	v_exp_f32_e32 v25, v105
	v_exp_f32_e32 v26, v106
	v_exp_f32_e32 v27, v107
	s_waitcnt lgkmcnt(0)
	v_mfma_f32_32x32x16_bf16 v[32:47], v[96:99], v[2:5], v[32:47]
	v_exp_f32_e32 v28, v108
	v_exp_f32_e32 v29, v109
	v_exp_f32_e32 v30, v110
	v_exp_f32_e32 v31, v111
	s_and_b64 vcc, exec, s[2:3]
	s_cbranch_vccnz .Latt_oresc0
.LBB0_685:
	s_mulk_i32 s71, 0x3400
	s_add_i32 s3, s71, 0
	s_xor_b32 s2, s69, 2
	v_add_u32_e32 v0, s3, v192
	s_mulk_i32 s2, 0x2400
	s_waitcnt vmcnt(5)
	ds_write_b128 v0, v[168:171]
	v_add_u32_e32 v0, s3, v185
	s_waitcnt vmcnt(4)
	ds_write_b128 v0, v[164:167] offset:128
	v_add_u32_e32 v0, s2, v193
	s_add_i32 s2, s67, 6
	s_min_i32 s2, s2, s66
	s_mov_b32 s3, s47
	v_add_u32_e32 v0, 0xd000, v0
	s_lshl_b64 s[4:5], s[2:3], 16
	s_lshl_b64 s[2:3], s[2:3], 12
	s_waitcnt vmcnt(3)
	ds_write2_b64 v0, v[160:161], v[162:163] offset1:2
	v_lshl_add_u64 v[2:3], v[186:187], 0, s[4:5]
	v_lshl_add_u64 v[4:5], v[188:189], 0, s[2:3]
	s_lshl_b64 s[2:3], s[46:47], 7
	global_load_dwordx4 v[168:171], v[2:3], off
	global_load_dwordx4 v[164:167], v[4:5], off
	v_lshl_add_u64 v[2:3], v[190:191], 0, s[2:3]
	global_load_dwordx4 v[160:163], v[2:3], off
	s_add_i32 s46, s67, 2
	s_cmp_ge_i32 s67, s65
	s_cbranch_scc1 .LBB0_696
	s_and_b32 s2, s46, 2
	s_mulk_i32 s2, 0x3400
	v_add_u32_e32 v0, s2, v196
	ds_read_b128 v[2:5], v0
	ds_read_b128 v[6:9], v0 offset:6656
	s_waitcnt lgkmcnt(1)
	v_mfma_f32_32x32x16_bf16 v[112:127], v[2:5], v[128:131], v[48:63]
	ds_read_b128 v[10:13], v0 offset:32
	ds_read_b128 v[202:205], v0 offset:6688
	v_add_f32_e32 v14, 0, v80
	v_add_f32_e32 v14, v81, v14
	v_cvt_pk_bf16_f32 v176, v80, v81
	s_waitcnt lgkmcnt(2)
	v_mfma_f32_32x32x16_bf16 v[96:111], v[6:9], v[128:131], v[48:63]
	v_add_f32_e32 v2, v82, v14
	v_add_f32_e32 v2, v83, v2
	v_add_f32_e32 v14, v84, v2
	v_cvt_pk_bf16_f32 v177, v82, v83
	s_waitcnt lgkmcnt(1)
	v_mfma_f32_32x32x16_bf16 v[112:127], v[10:13], v[132:135], v[112:127]
	ds_read_b128 v[2:5], v0 offset:64
	ds_read_b128 v[6:9], v0 offset:6720
	v_add_f32_e32 v14, v85, v14
	v_add_f32_e32 v14, v86, v14
	v_add_f32_e32 v14, v87, v14
	v_cvt_pk_bf16_f32 v178, v84, v85
	v_cvt_pk_bf16_f32 v179, v86, v87
	s_waitcnt lgkmcnt(2)
	v_mfma_f32_32x32x16_bf16 v[96:111], v[202:205], v[132:135], v[96:111]
	v_add_f32_e32 v10, v88, v14
	v_add_f32_e32 v11, v89, v10
	v_cvt_pk_bf16_f32 v10, v88, v89
	s_waitcnt lgkmcnt(1)
	v_mfma_f32_32x32x16_bf16 v[112:127], v[2:5], v[136:139], v[112:127]
	ds_read_b128 v[80:83], v0 offset:96
	ds_read_b128 v[202:205], v0 offset:6752
	v_add_f32_e32 v11, v90, v11
	v_add_f32_e32 v11, v91, v11
	v_add_f32_e32 v12, v92, v11
	v_cvt_pk_bf16_f32 v11, v90, v91
	s_waitcnt lgkmcnt(2)
	v_mfma_f32_32x32x16_bf16 v[96:111], v[6:9], v[136:139], v[96:111]
	v_add_f32_e32 v2, v93, v12
	v_add_f32_e32 v2, v94, v2
	v_add_f32_e32 v14, v95, v2
	v_cvt_pk_bf16_f32 v12, v92, v93
	v_cvt_pk_bf16_f32 v13, v94, v95
	s_waitcnt lgkmcnt(1)
	v_mfma_f32_32x32x16_bf16 v[112:127], v[80:83], v[140:143], v[112:127]
	ds_read_b128 v[2:5], v0 offset:128
	ds_read_b128 v[206:209], v0 offset:6784
	v_add_f32_e32 v6, v16, v14
	v_add_f32_e32 v7, v17, v6
	v_cvt_pk_bf16_f32 v6, v16, v17
	s_waitcnt lgkmcnt(2)
	v_mfma_f32_32x32x16_bf16 v[96:111], v[202:205], v[140:143], v[96:111]
	v_add_f32_e32 v7, v18, v7
	v_add_f32_e32 v7, v19, v7
	v_add_f32_e32 v8, v20, v7
	v_cvt_pk_bf16_f32 v7, v18, v19
	s_waitcnt lgkmcnt(1)
	v_mfma_f32_32x32x16_bf16 v[112:127], v[2:5], v[144:147], v[112:127]
	ds_read_b128 v[14:17], v0 offset:160
	ds_read_b128 v[80:83], v0 offset:6816
	v_add_f32_e32 v0, v21, v8
	v_add_f32_e32 v0, v22, v0
	v_add_f32_e32 v0, v23, v0
	v_cvt_pk_bf16_f32 v8, v20, v21
	v_cvt_pk_bf16_f32 v9, v22, v23
	s_waitcnt lgkmcnt(2)
	v_mfma_f32_32x32x16_bf16 v[96:111], v[206:209], v[144:147], v[96:111]
	v_add_f32_e32 v0, v24, v0
	v_add_f32_e32 v0, v25, v0
	v_cvt_pk_bf16_f32 v2, v24, v25
	s_waitcnt lgkmcnt(1)
	v_mfma_f32_32x32x16_bf16 v[112:127], v[14:17], v[148:151], v[112:127]
	v_add_f32_e32 v0, v26, v0
	v_add_f32_e32 v0, v27, v0
	v_add_f32_e32 v0, v28, v0
	v_cvt_pk_bf16_f32 v3, v26, v27
	s_waitcnt lgkmcnt(0)
	v_mfma_f32_32x32x16_bf16 v[96:111], v[80:83], v[148:151], v[96:111]
	v_add_f32_e32 v0, v29, v0
	v_add_f32_e32 v0, v30, v0
	v_add_f32_e32 v0, v31, v0
	v_cvt_pk_bf16_f32 v4, v28, v29
	v_cvt_pk_bf16_f32 v5, v30, v31
	s_mul_i32 s4, s69, 0x2400
	v_add_u32_e32 v206, s4, v200
	ds_read_b128 v[16:19], v206 offset:53248
	ds_read_b128 v[202:205], v206 offset:57856
	s_cmp_ge_i32 s70, s65
	v_add_f32_e32 v201, v201, v0
	s_cbranch_scc1 .LBB0_693
	s_cmp_le_i32 s68, s63
	s_cbranch_scc0 .Latt_mask1

.Latt_oresc1:
	v_pk_mul_f32 v[78:79], v[0:1], v[78:79] op_sel_hi:[0,1]
	v_pk_mul_f32 v[76:77], v[0:1], v[76:77] op_sel_hi:[0,1]
	v_pk_mul_f32 v[74:75], v[0:1], v[74:75] op_sel_hi:[0,1]
	v_pk_mul_f32 v[72:73], v[0:1], v[72:73] op_sel_hi:[0,1]
	v_pk_mul_f32 v[70:71], v[0:1], v[70:71] op_sel_hi:[0,1]
	v_pk_mul_f32 v[68:69], v[0:1], v[68:69] op_sel_hi:[0,1]
	v_pk_mul_f32 v[66:67], v[0:1], v[66:67] op_sel_hi:[0,1]
	v_pk_mul_f32 v[64:65], v[0:1], v[64:65] op_sel_hi:[0,1]
	v_pk_mul_f32 v[46:47], v[0:1], v[46:47] op_sel_hi:[0,1]
	v_pk_mul_f32 v[44:45], v[0:1], v[44:45] op_sel_hi:[0,1]
	v_pk_mul_f32 v[42:43], v[0:1], v[42:43] op_sel_hi:[0,1]
	v_pk_mul_f32 v[40:41], v[0:1], v[40:41] op_sel_hi:[0,1]
	v_pk_mul_f32 v[38:39], v[0:1], v[38:39] op_sel_hi:[0,1]
	v_pk_mul_f32 v[36:37], v[0:1], v[36:37] op_sel_hi:[0,1]
	v_pk_mul_f32 v[34:35], v[0:1], v[34:35] op_sel_hi:[0,1]
	v_pk_mul_f32 v[32:33], v[0:1], v[32:33] op_sel_hi:[0,1]
	s_branch .LBB0_696
.Latt_resc1:
	ds_bpermute_b32 v14, v198, v0
	s_mov_b64 s[2:3], -1
	s_waitcnt lgkmcnt(0)
	v_max3_f32 v14, v0, v14, 0
	v_exp_f32_e64 v0, -v14
	v_add_f32_e32 v199, v199, v14
	v_xor_b32_e32 v48, 0x80000000, v199
	v_sub_f32_e32 v127, v127, v14
	v_sub_f32_e32 v126, v126, v14
	v_sub_f32_e32 v125, v125, v14
	v_sub_f32_e32 v124, v124, v14
	v_sub_f32_e32 v123, v123, v14
	v_mul_f32_e32 v201, v201, v0
	v_sub_f32_e32 v122, v122, v14
	v_sub_f32_e32 v121, v121, v14
	v_sub_f32_e32 v120, v120, v14
	v_sub_f32_e32 v119, v119, v14
	v_sub_f32_e32 v118, v118, v14
	v_sub_f32_e32 v117, v117, v14
	v_sub_f32_e32 v116, v116, v14
	v_sub_f32_e32 v115, v115, v14
	v_sub_f32_e32 v114, v114, v14
	v_sub_f32_e32 v113, v113, v14
	v_sub_f32_e32 v112, v112, v14
	v_sub_f32_e32 v111, v111, v14
	v_sub_f32_e32 v110, v110, v14
	v_sub_f32_e32 v109, v109, v14
	v_sub_f32_e32 v108, v108, v14
	v_sub_f32_e32 v107, v107, v14
	v_sub_f32_e32 v106, v106, v14
	v_sub_f32_e32 v105, v105, v14
	v_sub_f32_e32 v104, v104, v14
	v_sub_f32_e32 v103, v103, v14
	v_sub_f32_e32 v102, v102, v14
	v_sub_f32_e32 v101, v101, v14
	v_sub_f32_e32 v100, v100, v14
	v_sub_f32_e32 v99, v99, v14
	v_sub_f32_e32 v98, v98, v14
	v_sub_f32_e32 v97, v97, v14
	v_sub_f32_e32 v96, v96, v14
	v_mov_b32_e32 v49, v48
	v_mov_b32_e32 v50, v48
	v_mov_b32_e32 v51, v48
	v_mov_b32_e32 v52, v48
	v_mov_b32_e32 v53, v48
	v_mov_b32_e32 v54, v48
	v_mov_b32_e32 v55, v48
	v_mov_b32_e32 v56, v48
	v_mov_b32_e32 v57, v48
	v_mov_b32_e32 v58, v48
	v_mov_b32_e32 v59, v48
	v_mov_b32_e32 v60, v48
	v_mov_b32_e32 v61, v48
	v_mov_b32_e32 v62, v48
	v_mov_b32_e32 v63, v48
	s_branch .LBB0_694
.Latt_mask1:
	v_add_u32_e32 v0, s68, v197
	v_subrev_u32_e32 v15, 31, v0
	v_subrev_u32_e32 v14, 63, v0
	v_cmp_le_i32_e64 s[2:3], v15, v184
	v_cmp_le_i32_e32 vcc, v14, v184
	s_nop 0
	v_cndmask_b32_e64 v96, v194, v96, s[2:3]
	v_cmp_lt_i32_e64 s[2:3], v14, v184
	v_subrev_u32_e32 v14, 30, v0
	v_cmp_le_i32_e64 s[4:5], v14, v184
	v_subrev_u32_e32 v14, 61, v0
	s_nop 0
	v_cndmask_b32_e64 v97, v194, v97, s[4:5]
	v_cmp_le_i32_e64 s[4:5], v14, v184
	v_subrev_u32_e32 v14, 29, v0
	v_cmp_le_i32_e64 s[6:7], v14, v184
	v_subrev_u32_e32 v14, 60, v0
	s_nop 0
	v_cndmask_b32_e64 v98, v194, v98, s[6:7]
	v_cmp_le_i32_e64 s[6:7], v14, v184
	v_subrev_u32_e32 v14, 28, v0
	v_cmp_le_i32_e64 s[8:9], v14, v184
	v_subrev_u32_e32 v14, 55, v0
	s_nop 0
	v_cndmask_b32_e64 v99, v194, v99, s[8:9]
	v_cmp_le_i32_e64 s[8:9], v14, v184
	v_subrev_u32_e32 v14, 23, v0
	v_cmp_le_i32_e64 s[10:11], v14, v184
	v_subrev_u32_e32 v14, 54, v0
	s_nop 0
	v_cndmask_b32_e64 v100, v194, v100, s[10:11]
	v_cmp_le_i32_e64 s[10:11], v14, v184
	v_subrev_u32_e32 v14, 22, v0
	v_cmp_le_i32_e64 s[12:13], v14, v184
	v_subrev_u32_e32 v14, 53, v0
	s_nop 0
	v_cndmask_b32_e64 v101, v194, v101, s[12:13]
	v_cmp_le_i32_e64 s[12:13], v14, v184
	v_subrev_u32_e32 v14, 21, v0
	v_cmp_le_i32_e64 s[14:15], v14, v184
	v_subrev_u32_e32 v14, 52, v0
	s_nop 0
	v_cndmask_b32_e64 v102, v194, v102, s[14:15]
	v_cmp_le_i32_e64 s[14:15], v14, v184
	v_subrev_u32_e32 v14, 20, v0
	v_cmp_le_i32_e64 s[16:17], v14, v184
	v_subrev_u32_e32 v14, 47, v0
	s_nop 0
	v_cndmask_b32_e64 v103, v194, v103, s[16:17]
	v_cmp_le_i32_e64 s[16:17], v14, v184
	v_add_u32_e32 v14, -15, v0
	v_cmp_le_i32_e64 s[18:19], v14, v184
	v_subrev_u32_e32 v14, 46, v0
	s_nop 0
	v_cndmask_b32_e64 v104, v194, v104, s[18:19]
	v_cmp_le_i32_e64 s[18:19], v14, v184
	v_add_u32_e32 v14, -14, v0
	v_cmp_le_i32_e64 s[20:21], v14, v184
	v_subrev_u32_e32 v14, 45, v0
	s_nop 0
	v_cndmask_b32_e64 v105, v194, v105, s[20:21]
	v_cmp_le_i32_e64 s[20:21], v14, v184
	v_add_u32_e32 v14, -13, v0
	v_cmp_le_i32_e64 s[22:23], v14, v184
	v_subrev_u32_e32 v14, 44, v0
	s_nop 0
	v_cndmask_b32_e64 v106, v194, v106, s[22:23]
	v_cmp_le_i32_e64 s[22:23], v14, v184
	v_add_u32_e32 v14, -12, v0
	v_cmp_le_i32_e64 s[24:25], v14, v184
	v_subrev_u32_e32 v14, 39, v0
	s_nop 0
	v_cndmask_b32_e64 v107, v194, v107, s[24:25]
	v_cmp_le_i32_e64 s[24:25], v14, v184
	v_add_u32_e32 v14, -7, v0
	v_cmp_le_i32_e64 s[26:27], v14, v184
	v_subrev_u32_e32 v14, 38, v0
	s_nop 0
	v_cndmask_b32_e64 v108, v194, v108, s[26:27]
	v_cmp_le_i32_e64 s[26:27], v14, v184
	v_add_u32_e32 v14, -6, v0
	v_cmp_le_i32_e64 s[28:29], v14, v184
	v_subrev_u32_e32 v14, 37, v0
	s_nop 0
	v_cndmask_b32_e64 v109, v194, v109, s[28:29]
	v_cmp_le_i32_e64 s[28:29], v14, v184
	v_add_u32_e32 v14, -5, v0
	v_cmp_le_i32_e64 s[30:31], v14, v184
	v_subrev_u32_e32 v14, 36, v0
	v_add_u32_e32 v0, -4, v0
	v_cndmask_b32_e64 v110, v194, v110, s[30:31]
	v_cmp_le_i32_e64 s[30:31], v14, v184
	v_cmp_gt_i32_e64 s[34:35], v0, v184
	s_and_saveexec_b64 s[48:49], s[34:35]
	v_mov_b32_e32 v111, s59
	s_or_b64 exec, exec, s[48:49]
	v_cndmask_b32_e64 v113, v194, v113, s[2:3]
	v_cndmask_b32_e32 v112, v194, v112, vcc
	v_cndmask_b32_e64 v114, v194, v114, s[4:5]
	v_cndmask_b32_e64 v115, v194, v115, s[6:7]
	v_cndmask_b32_e64 v116, v194, v116, s[8:9]
	v_cndmask_b32_e64 v117, v194, v117, s[10:11]
	v_cndmask_b32_e64 v118, v194, v118, s[12:13]
	v_cndmask_b32_e64 v119, v194, v119, s[14:15]
	v_cndmask_b32_e64 v120, v194, v120, s[16:17]
	v_cndmask_b32_e64 v121, v194, v121, s[18:19]
	v_cndmask_b32_e64 v122, v194, v122, s[20:21]
	v_cndmask_b32_e64 v123, v194, v123, s[22:23]
	v_cndmask_b32_e64 v124, v194, v124, s[24:25]
	v_cndmask_b32_e64 v125, v194, v125, s[26:27]
	v_cndmask_b32_e64 v126, v194, v126, s[28:29]
	v_cndmask_b32_e64 v127, v194, v127, s[30:31]
	s_branch .LBB0_691

.Latt_mask0:
	v_add_u32_e32 v0, s68, v197
	v_add_u32_e32 v15, 0xffffffa1, v0
	v_add_u32_e32 v14, 0xffffff81, v0
	v_cmp_le_i32_e64 s[2:3], v15, v184
	v_cmp_le_i32_e32 vcc, v14, v184
	s_nop 0
	v_cndmask_b32_e64 v96, v194, v96, s[2:3]
	v_cmp_lt_i32_e64 s[2:3], v14, v184
	v_add_u32_e32 v14, 0xffffffa2, v0
	v_cmp_le_i32_e64 s[4:5], v14, v184
	v_add_u32_e32 v14, 0xffffff83, v0
	s_nop 0
	v_cndmask_b32_e64 v97, v194, v97, s[4:5]
	v_cmp_le_i32_e64 s[4:5], v14, v184
	v_add_u32_e32 v14, 0xffffffa3, v0
	v_cmp_le_i32_e64 s[6:7], v14, v184
	v_add_u32_e32 v14, 0xffffff84, v0
	s_nop 0
	v_cndmask_b32_e64 v98, v194, v98, s[6:7]
	v_cmp_le_i32_e64 s[6:7], v14, v184
	v_add_u32_e32 v14, 0xffffffa4, v0
	v_cmp_le_i32_e64 s[8:9], v14, v184
	v_add_u32_e32 v14, 0xffffff89, v0
	s_nop 0
	v_cndmask_b32_e64 v99, v194, v99, s[8:9]
	v_cmp_le_i32_e64 s[8:9], v14, v184
	v_add_u32_e32 v14, 0xffffffa9, v0
	v_cmp_le_i32_e64 s[10:11], v14, v184
	v_add_u32_e32 v14, 0xffffff8a, v0
	s_nop 0
	v_cndmask_b32_e64 v100, v194, v100, s[10:11]
	v_cmp_le_i32_e64 s[10:11], v14, v184
	v_add_u32_e32 v14, 0xffffffaa, v0
	v_cmp_le_i32_e64 s[12:13], v14, v184
	v_add_u32_e32 v14, 0xffffff8b, v0
	s_nop 0
	v_cndmask_b32_e64 v101, v194, v101, s[12:13]
	v_cmp_le_i32_e64 s[12:13], v14, v184
	v_add_u32_e32 v14, 0xffffffab, v0
	v_cmp_le_i32_e64 s[14:15], v14, v184
	v_add_u32_e32 v14, 0xffffff8c, v0
	s_nop 0
	v_cndmask_b32_e64 v102, v194, v102, s[14:15]
	v_cmp_le_i32_e64 s[14:15], v14, v184
	v_add_u32_e32 v14, 0xffffffac, v0
	v_cmp_le_i32_e64 s[16:17], v14, v184
	v_add_u32_e32 v14, 0xffffff91, v0
	s_nop 0
	v_cndmask_b32_e64 v103, v194, v103, s[16:17]
	v_cmp_le_i32_e64 s[16:17], v14, v184
	v_add_u32_e32 v14, 0xffffffb1, v0
	v_cmp_le_i32_e64 s[18:19], v14, v184
	v_add_u32_e32 v14, 0xffffff92, v0
	s_nop 0
	v_cndmask_b32_e64 v104, v194, v104, s[18:19]
	v_cmp_le_i32_e64 s[18:19], v14, v184
	v_add_u32_e32 v14, 0xffffffb2, v0
	v_cmp_le_i32_e64 s[20:21], v14, v184
	v_add_u32_e32 v14, 0xffffff93, v0
	s_nop 0
	v_cndmask_b32_e64 v105, v194, v105, s[20:21]
	v_cmp_le_i32_e64 s[20:21], v14, v184
	v_add_u32_e32 v14, 0xffffffb3, v0
	v_cmp_le_i32_e64 s[22:23], v14, v184
	v_add_u32_e32 v14, 0xffffff94, v0
	s_nop 0
	v_cndmask_b32_e64 v106, v194, v106, s[22:23]
	v_cmp_le_i32_e64 s[22:23], v14, v184
	v_add_u32_e32 v14, 0xffffffb4, v0
	v_cmp_le_i32_e64 s[24:25], v14, v184
	v_add_u32_e32 v14, 0xffffff99, v0
	s_nop 0
	v_cndmask_b32_e64 v107, v194, v107, s[24:25]
	v_cmp_le_i32_e64 s[24:25], v14, v184
	v_add_u32_e32 v14, 0xffffffb9, v0
	v_cmp_le_i32_e64 s[26:27], v14, v184
	v_add_u32_e32 v14, 0xffffff9a, v0
	s_nop 0
	v_cndmask_b32_e64 v108, v194, v108, s[26:27]
	v_cmp_le_i32_e64 s[26:27], v14, v184
	v_add_u32_e32 v14, 0xffffffba, v0
	v_cmp_le_i32_e64 s[28:29], v14, v184
	v_add_u32_e32 v14, 0xffffff9b, v0
	s_nop 0
	v_cndmask_b32_e64 v109, v194, v109, s[28:29]
	v_cmp_le_i32_e64 s[28:29], v14, v184
	v_add_u32_e32 v14, 0xffffffbb, v0
	v_cmp_le_i32_e64 s[30:31], v14, v184
	v_add_u32_e32 v14, 0xffffff9c, v0
	v_add_u32_e32 v0, 0xffffffbc, v0
	v_cndmask_b32_e64 v110, v194, v110, s[30:31]
	v_cmp_le_i32_e64 s[30:31], v14, v184
	v_cmp_gt_i32_e64 s[34:35], v0, v184
	s_and_saveexec_b64 s[48:49], s[34:35]
	v_mov_b32_e32 v111, s59
	s_or_b64 exec, exec, s[48:49]
	v_cndmask_b32_e64 v113, v194, v113, s[2:3]
	v_cndmask_b32_e32 v112, v194, v112, vcc
	v_cndmask_b32_e64 v114, v194, v114, s[4:5]
	v_cndmask_b32_e64 v115, v194, v115, s[6:7]
	v_cndmask_b32_e64 v116, v194, v116, s[8:9]
	v_cndmask_b32_e64 v117, v194, v117, s[10:11]
	v_cndmask_b32_e64 v118, v194, v118, s[12:13]
	v_cndmask_b32_e64 v119, v194, v119, s[14:15]
	v_cndmask_b32_e64 v120, v194, v120, s[16:17]
	v_cndmask_b32_e64 v121, v194, v121, s[18:19]
	v_cndmask_b32_e64 v122, v194, v122, s[20:21]
	v_cndmask_b32_e64 v123, v194, v123, s[22:23]
	v_cndmask_b32_e64 v124, v194, v124, s[24:25]
	v_cndmask_b32_e64 v125, v194, v125, s[26:27]
	v_cndmask_b32_e64 v126, v194, v126, s[28:29]
	v_cndmask_b32_e64 v127, v194, v127, s[30:31]
	s_branch .LBB0_680
